# lever 7: scan S2 tile loads in SGPR-base+VGPR-offset form (address adds on the scalar unit); redundant per-chunk SGPR restores dropped
# baseline (speedup 1.0000x reference)
; DI void ssd_scan_phase(bf16_t* P, const bf16_t* BT, const bf16_t* Cc, const bf16_t* CB, const float* dt, const float* acs,
;                        const float* cw, const float* cb, const float* Dp, char* lds, bool dry, int mode, float* Sbuf) {
;     ...
;       if (c + 1 < c1) {
;         if (c + 2 < c1 && tid < 128) { nacs = (acs + (t0 + 256) * 32 + hh)[tid * 32]; ndt = (dt + (t0 + 256) * 32 + hh)[tid * 32]; }
;         const size_t cbi = cbi0 + (size_t)(c + 1) * 65536;
;         const bf16_t* Cq = Cc + cbi; const bf16_t* Bq = BT + cbi; const bf16_t* CBq = CB + cbi;
; #pragma unroll
;         for (int j = 0; j < 4; ++j) { rB[j] = *(const u32x4*)(Bq + toff + j * 4096); if (mode == 0) { rC[j] = *(const u32x4*)(Cq + toff + j * 4096); rCB[j] = *(const u32x4*)(CBq + toff + j * 4096); } }
;         const bf16_t* Xq = P + (t0 + 125) * 5120 + 2048 + pcol;
; #pragma unroll
;         for (int kk = 0; kk < 5; ++kk) { if (wave >= 4) rX[kk] = *(const u32x4*)(Xq + xoff + kk * 5120); }
.LBB0_1085:
	s_or_b64 exec, exec, s[80:81]
	s_and_b64 vcc, exec, s[56:57]
	s_add_u32 s100, s74, 0x20000
	s_addc_u32 s101, s75, 0
	global_load_dwordx4 v[60:63], v168, s[100:101]
	s_cbranch_vccnz .Ls2_m1
	s_add_u32 s100, s74, 0x1020000
	s_addc_u32 s101, s75, 0
	global_load_dwordx4 v[52:55], v168, s[100:101]
	v_lshrrev_b32_e32 v26, 4, v200
	v_and_b32_e32 v27, 15, v200
	v_lshlrev_b32_e32 v27, 4, v27
	v_lshl_or_b32 v26, v26, 8, v27
	v_sub_u32_e32 v26, v168, v26
	v_lshrrev_b32_e32 v28, 2, v200
	v_sub_u32_e32 v28, 0x7f, v28
	v_and_b32_e32 v29, 3, v200
	v_lshlrev_b32_e32 v29, 4, v29
	v_lshl_or_b32 v28, v28, 8, v29
	v_add_u32_e32 v26, v26, v28
	s_add_u32 s100, s76, 0x20000
	s_addc_u32 s101, s77, 0
	global_load_dwordx4 v[56:59], v26, s[100:101]
	s_add_u32 s100, s74, 0x22000
	s_addc_u32 s101, s75, 0
	global_load_dwordx4 v[76:79], v168, s[100:101]
	s_add_u32 s100, s74, 0x1022000
	s_addc_u32 s101, s75, 0
	global_load_dwordx4 v[64:67], v168, s[100:101]
	s_add_u32 s100, s76, 0x20000
	s_addc_u32 s101, s77, 0
	global_load_dwordx4 v[68:71], v26, s[100:101] offset:64
	s_add_u32 s100, s74, 0x24000
	s_addc_u32 s101, s75, 0
	global_load_dwordx4 v[92:95], v168, s[100:101]
	s_add_u32 s100, s74, 0x1024000
	s_addc_u32 s101, s75, 0
	global_load_dwordx4 v[72:75], v168, s[100:101]
	s_add_u32 s100, s76, 0x20000
	s_addc_u32 s101, s77, 0
	global_load_dwordx4 v[80:83], v26, s[100:101] offset:128
	s_add_u32 s100, s74, 0x26000
	s_addc_u32 s101, s75, 0
	global_load_dwordx4 v[104:107], v168, s[100:101]
	s_add_u32 s100, s74, 0x1026000
	s_addc_u32 s101, s75, 0
	global_load_dwordx4 v[84:87], v168, s[100:101]
	s_add_u32 s100, s76, 0x20000
	s_addc_u32 s101, s77, 0
	global_load_dwordx4 v[88:91], v26, s[100:101] offset:192
	s_branch .LBB0_1093
.Ls2_m1:
	s_add_u32 s100, s74, 0x22000
	s_addc_u32 s101, s75, 0
	global_load_dwordx4 v[76:79], v168, s[100:101]
	s_add_u32 s100, s74, 0x24000
	s_addc_u32 s101, s75, 0
	global_load_dwordx4 v[92:95], v168, s[100:101]
	s_add_u32 s100, s74, 0x26000
	s_addc_u32 s101, s75, 0
	global_load_dwordx4 v[104:107], v168, s[100:101]
.LBB0_1093:
	v_mov_b64_e32 v[20:21], s[18:19]
	v_mad_u64_u32 v[20:21], s[80:81], v172, s96, v[20:21]
	v_mad_i32_i24 v21, v173, s96, v21
	v_lshl_add_u64 v[20:21], v[20:21], 0, s[34:35]
	v_lshl_add_u64 v[20:21], v[130:131], 1, v[20:21]
	s_mov_b64 s[80:81], 0x139800
	v_lshl_add_u64 v[20:21], v[20:21], 0, s[80:81]
	s_and_saveexec_b64 s[80:81], s[42:43]
	s_cbranch_execnz .LBB0_1115
	s_or_b64 exec, exec, s[80:81]
	s_and_saveexec_b64 s[80:81], s[42:43]
	s_cbranch_execnz .LBB0_1116

; __global__ void __launch_bounds__(512) mega(Params p, int ph_lo, int ph_hi) {
	.amdhsa_kernel _Z4mega6Paramsii
		.amdhsa_group_segment_fixed_size 0
		.amdhsa_private_segment_fixed_size 0
		.amdhsa_kernarg_size 504
		.amdhsa_user_sgpr_count 2
		.amdhsa_user_sgpr_dispatch_ptr 0
		.amdhsa_user_sgpr_queue_ptr 0
		.amdhsa_user_sgpr_kernarg_segment_ptr 1
		.amdhsa_user_sgpr_dispatch_id 0
		.amdhsa_user_sgpr_kernarg_preload_length 0
		.amdhsa_user_sgpr_kernarg_preload_offset 0
		.amdhsa_user_sgpr_private_segment_size 0
		.amdhsa_uses_dynamic_stack 0
		.amdhsa_enable_private_segment 0
		.amdhsa_system_sgpr_workgroup_id_x 1
		.amdhsa_system_sgpr_workgroup_id_y 0
		.amdhsa_system_sgpr_workgroup_id_z 0
		.amdhsa_system_sgpr_workgroup_info 0
		.amdhsa_system_vgpr_workitem_id 2
		.amdhsa_next_free_vgpr 256
		.amdhsa_next_free_sgpr 102
		.amdhsa_accum_offset 256
		.amdhsa_reserve_vcc 1
		.amdhsa_float_round_mode_32 0
		.amdhsa_float_round_mode_16_64 0
		.amdhsa_float_denorm_mode_32 3
		.amdhsa_float_denorm_mode_16_64 3
		.amdhsa_dx10_clamp 1
		.amdhsa_ieee_mode 1
		.amdhsa_fp16_overflow 0
		.amdhsa_tg_split 0
		.amdhsa_exception_fp_ieee_invalid_op 0
		.amdhsa_exception_fp_denorm_src 0
		.amdhsa_exception_fp_ieee_div_zero 0
		.amdhsa_exception_fp_ieee_overflow 0
		.amdhsa_exception_fp_ieee_underflow 0
		.amdhsa_exception_fp_ieee_inexact 0
		.amdhsa_exception_int_div_zero 0
	.end_amdhsa_kernel

; __global__ void __launch_bounds__(512) mega(Params p, int ph_lo, int ph_hi) {
;   extern __shared__ __attribute__((aligned(16))) char lds[];
amdhsa.kernels:
  - .agpr_count:     0
    .args:
      - .offset:         0
        .size:           240
        .value_kind:     by_value
      - .offset:         240
        .size:           4
        .value_kind:     by_value
      - .offset:         244
        .size:           4
        .value_kind:     by_value
      - .offset:         248
        .size:           4
        .value_kind:     hidden_block_count_x
      - .offset:         252
        .size:           4
        .value_kind:     hidden_block_count_y
      - .offset:         256
        .size:           4
        .value_kind:     hidden_block_count_z
      - .offset:         260
        .size:           2
        .value_kind:     hidden_group_size_x
      - .offset:         262
        .size:           2
        .value_kind:     hidden_group_size_y
      - .offset:         264
        .size:           2
        .value_kind:     hidden_group_size_z
      - .offset:         266
        .size:           2
        .value_kind:     hidden_remainder_x
      - .offset:         268
        .size:           2
        .value_kind:     hidden_remainder_y
      - .offset:         270
        .size:           2
        .value_kind:     hidden_remainder_z
      - .offset:         288
        .size:           8
        .value_kind:     hidden_global_offset_x
      - .offset:         296
        .size:           8
        .value_kind:     hidden_global_offset_y
      - .offset:         304
        .size:           8
        .value_kind:     hidden_global_offset_z
      - .offset:         312
        .size:           2
        .value_kind:     hidden_grid_dims
      - .offset:         336
        .size:           8
        .value_kind:     hidden_multigrid_sync_arg
      - .offset:         368
        .size:           4
        .value_kind:     hidden_dynamic_lds_size
    .group_segment_fixed_size: 0
    .kernarg_segment_align: 8
    .kernarg_segment_size: 504
    .language:       OpenCL C
    .language_version:
      - 2
      - 0
    .max_flat_workgroup_size: 512
    .name:           _Z4mega6Paramsii
    .private_segment_fixed_size: 0
    .sgpr_count:     108
    .sgpr_spill_count: 229
    .symbol:         _Z4mega6Paramsii.kd
    .uniform_work_group_size: 1
    .uses_dynamic_stack: false
    .vgpr_count:     256
    .vgpr_spill_count: 0
    .wavefront_size: 64
